# GEMM k-loops: loop-carried pointer/counter SALU moved ahead of the loop-back barrier (strategy 9 on the GEMM)
# baseline (speedup 1.0000x reference)
.LBB0_176:
	s_add_u32 s2, s14, 0xfffc0080
	s_addc_u32 s3, s15, -1
	s_add_i32 s47, 0, 0x10000
	s_cmp_eq_u32 s46, 12
	s_cselect_b32 s25, s7, s3
	s_cselect_b32 s24, s11, s2
	v_add_u32_e32 v0, s47, v155
	s_cselect_b32 s3, s13, s33
	s_cselect_b32 s2, s29, s31
	s_add_i32 s54, 0, 0x14000
	ds_read_b128 v[50:53], v0
	ds_read_b128 v[54:57], v0 offset:1024
	ds_read_b128 v[58:61], v0 offset:2048
	ds_read_b128 v[62:65], v0 offset:3072
	v_add_u32_e32 v0, s54, v155
	ds_read_b128 v[176:179], v0
	ds_read_b128 v[188:191], v0 offset:1024
	ds_read_b128 v[192:195], v0 offset:2048
	ds_read_b128 v[196:199], v0 offset:3072
	v_lshl_add_u64 v[180:181], s[14:15], 0, v[170:171]
	s_add_i32 m0, s90, 0xc000
	ds_read_b128 v[200:203], v186
	ds_read_b128 v[204:207], v186 offset:1024
	ds_read_b128 v[226:229], v186 offset:2048
	ds_read_b128 v[230:233], v186 offset:3072
	ds_read_b128 v[234:237], v186 offset:4096
	ds_read_b128 v[238:241], v186 offset:5120
	ds_read_b128 v[242:245], v186 offset:6144
	ds_read_b128 v[246:249], v186 offset:7168
	global_load_lds_dwordx4 v[180:181], off
	v_lshl_add_u64 v[180:181], s[14:15], 0, v[172:173]
	s_add_i32 m0, s90, 0xe000
	s_nop 0
	global_load_lds_dwordx4 v[180:181], off
	s_waitcnt vmcnt(8)
	s_waitcnt lgkmcnt(0)
	s_barrier
	s_setprio 1
	s_waitcnt lgkmcnt(0)
	v_mfma_f32_16x16x32_bf16 v[142:145], v[50:53], v[200:203], v[142:145]
	v_mfma_f32_16x16x32_bf16 v[138:141], v[58:61], v[200:203], v[138:141]
	v_mfma_f32_16x16x32_bf16 v[126:129], v[50:53], v[226:229], v[126:129]
	v_mfma_f32_16x16x32_bf16 v[122:125], v[58:61], v[226:229], v[122:125]
	v_mfma_f32_16x16x32_bf16 v[110:113], v[50:53], v[234:237], v[110:113]
	v_mfma_f32_16x16x32_bf16 v[106:109], v[58:61], v[234:237], v[106:109]
	v_mfma_f32_16x16x32_bf16 v[94:97], v[50:53], v[242:245], v[94:97]
	v_mfma_f32_16x16x32_bf16 v[90:93], v[58:61], v[242:245], v[90:93]
	v_mfma_f32_16x16x32_bf16 v[142:145], v[54:57], v[204:207], v[142:145]
	v_mfma_f32_16x16x32_bf16 v[138:141], v[62:65], v[204:207], v[138:141]
	v_mfma_f32_16x16x32_bf16 v[126:129], v[54:57], v[230:233], v[126:129]
	v_mfma_f32_16x16x32_bf16 v[122:125], v[62:65], v[230:233], v[122:125]
	v_mfma_f32_16x16x32_bf16 v[110:113], v[54:57], v[238:241], v[110:113]
	v_mfma_f32_16x16x32_bf16 v[106:109], v[62:65], v[238:241], v[106:109]
	v_mfma_f32_16x16x32_bf16 v[94:97], v[54:57], v[246:249], v[94:97]
	v_mfma_f32_16x16x32_bf16 v[90:93], v[62:65], v[246:249], v[90:93]
	s_setprio 0
	s_setprio 1
	v_mfma_f32_16x16x32_bf16 v[134:137], v[176:179], v[200:203], v[134:137]
	v_mfma_f32_16x16x32_bf16 v[130:133], v[192:195], v[200:203], v[130:133]
	v_mfma_f32_16x16x32_bf16 v[118:121], v[176:179], v[226:229], v[118:121]
	v_mfma_f32_16x16x32_bf16 v[114:117], v[192:195], v[226:229], v[114:117]
	v_mfma_f32_16x16x32_bf16 v[102:105], v[176:179], v[234:237], v[102:105]
	v_mfma_f32_16x16x32_bf16 v[98:101], v[192:195], v[234:237], v[98:101]
	v_mfma_f32_16x16x32_bf16 v[86:89], v[176:179], v[242:245], v[86:89]
	v_mfma_f32_16x16x32_bf16 v[82:85], v[192:195], v[242:245], v[82:85]
	v_mfma_f32_16x16x32_bf16 v[134:137], v[188:191], v[204:207], v[134:137]
	v_mfma_f32_16x16x32_bf16 v[130:133], v[196:199], v[204:207], v[130:133]
	v_mfma_f32_16x16x32_bf16 v[118:121], v[188:191], v[230:233], v[118:121]
	v_mfma_f32_16x16x32_bf16 v[114:117], v[196:199], v[230:233], v[114:117]
	v_mfma_f32_16x16x32_bf16 v[102:105], v[188:191], v[238:241], v[102:105]
	v_mfma_f32_16x16x32_bf16 v[98:101], v[196:199], v[238:241], v[98:101]
	v_mfma_f32_16x16x32_bf16 v[86:89], v[188:191], v[246:249], v[86:89]
	v_mfma_f32_16x16x32_bf16 v[82:85], v[196:199], v[246:249], v[82:85]
	s_setprio 0
	s_barrier
	s_add_i32 s47, s47, s42
	v_lshl_add_u64 v[180:181], s[2:3], 0, v[146:147]
	s_mov_b32 m0, s47
	ds_read_b128 v[200:203], v186 offset:16384
	ds_read_b128 v[204:207], v186 offset:17408
	ds_read_b128 v[226:229], v186 offset:18432
	ds_read_b128 v[230:233], v186 offset:19456
	ds_read_b128 v[234:237], v186 offset:20480
	ds_read_b128 v[238:241], v186 offset:21504
	ds_read_b128 v[242:245], v186 offset:22528
	ds_read_b128 v[246:249], v186 offset:23552
	global_load_lds_dwordx4 v[180:181], off
	s_add_i32 m0, s47, 0x2000
	s_add_u32 s58, s2, 0x40000
	v_lshl_add_u64 v[222:223], s[2:3], 0, v[148:149]
	s_addc_u32 s59, s3, 0
	s_add_i32 s47, s54, s42
	global_load_lds_dwordx4 v[222:223], off
	v_lshl_add_u64 v[224:225], s[58:59], 0, v[146:147]
	s_mov_b32 m0, s47
	v_lshl_add_u64 v[250:251], s[24:25], 0, v[148:149]
	global_load_lds_dwordx4 v[224:225], off
	v_lshl_add_u64 v[224:225], s[58:59], 0, v[148:149]
	s_add_i32 m0, s47, 0x2000
	s_nop 0
	global_load_lds_dwordx4 v[224:225], off
	v_lshl_add_u64 v[224:225], s[24:25], 0, v[146:147]
	s_mov_b32 m0, s90
	s_nop 0
	global_load_lds_dwordx4 v[224:225], off
	s_mov_b32 m0, s91
	s_nop 0
	global_load_lds_dwordx4 v[250:251], off
	s_waitcnt vmcnt(8)
	s_waitcnt lgkmcnt(0)
	s_barrier
	s_setprio 1
	s_waitcnt lgkmcnt(0)
	v_mfma_f32_16x16x32_bf16 v[78:81], v[50:53], v[200:203], v[78:81]
	v_mfma_f32_16x16x32_bf16 v[74:77], v[58:61], v[200:203], v[74:77]
	v_mfma_f32_16x16x32_bf16 v[46:49], v[50:53], v[226:229], v[46:49]
	v_mfma_f32_16x16x32_bf16 v[42:45], v[58:61], v[226:229], v[42:45]
	v_mfma_f32_16x16x32_bf16 v[30:33], v[50:53], v[234:237], v[30:33]
	v_mfma_f32_16x16x32_bf16 v[26:29], v[58:61], v[234:237], v[26:29]
	v_mfma_f32_16x16x32_bf16 v[14:17], v[50:53], v[242:245], v[14:17]
	v_mfma_f32_16x16x32_bf16 v[10:13], v[58:61], v[242:245], v[10:13]
	v_mfma_f32_16x16x32_bf16 v[78:81], v[54:57], v[204:207], v[78:81]
	v_mfma_f32_16x16x32_bf16 v[74:77], v[62:65], v[204:207], v[74:77]
	v_mfma_f32_16x16x32_bf16 v[46:49], v[54:57], v[230:233], v[46:49]
	v_mfma_f32_16x16x32_bf16 v[42:45], v[62:65], v[230:233], v[42:45]
	v_mfma_f32_16x16x32_bf16 v[30:33], v[54:57], v[238:241], v[30:33]
	v_mfma_f32_16x16x32_bf16 v[26:29], v[62:65], v[238:241], v[26:29]
	v_mfma_f32_16x16x32_bf16 v[14:17], v[54:57], v[246:249], v[14:17]
	v_mfma_f32_16x16x32_bf16 v[10:13], v[62:65], v[246:249], v[10:13]
	s_setprio 0
	s_setprio 1
	v_mfma_f32_16x16x32_bf16 v[38:41], v[176:179], v[226:229], v[38:41]
	v_mfma_f32_16x16x32_bf16 v[34:37], v[192:195], v[226:229], v[34:37]
	v_mfma_f32_16x16x32_bf16 v[22:25], v[176:179], v[234:237], v[22:25]
	v_mfma_f32_16x16x32_bf16 v[18:21], v[192:195], v[234:237], v[18:21]
	v_mfma_f32_16x16x32_bf16 v[6:9], v[176:179], v[242:245], v[6:9]
	v_mfma_f32_16x16x32_bf16 v[2:5], v[192:195], v[242:245], v[2:5]
	v_mfma_f32_16x16x32_bf16 v[50:53], v[176:179], v[200:203], v[70:73]
	v_mfma_f32_16x16x32_bf16 v[54:57], v[192:195], v[200:203], v[66:69]
	v_mfma_f32_16x16x32_bf16 v[38:41], v[188:191], v[230:233], v[38:41]
	v_mfma_f32_16x16x32_bf16 v[34:37], v[196:199], v[230:233], v[34:37]
	v_mfma_f32_16x16x32_bf16 v[22:25], v[188:191], v[238:241], v[22:25]
	v_mfma_f32_16x16x32_bf16 v[18:21], v[196:199], v[238:241], v[18:21]
	v_mfma_f32_16x16x32_bf16 v[6:9], v[188:191], v[246:249], v[6:9]
	v_mfma_f32_16x16x32_bf16 v[2:5], v[196:199], v[246:249], v[2:5]
	v_mfma_f32_16x16x32_bf16 v[50:53], v[188:191], v[204:207], v[50:53]
	v_mfma_f32_16x16x32_bf16 v[54:57], v[196:199], v[204:207], v[54:57]
	s_setprio 0
	s_barrier
	s_add_i32 s47, 0, 0x18000
	v_add_u32_e32 v0, s47, v155
	s_add_i32 s54, 0, 0x1c000
	ds_read_b128 v[58:61], v0
	ds_read_b128 v[62:65], v0 offset:1024
	ds_read_b128 v[66:69], v0 offset:2048
	ds_read_b128 v[70:73], v0 offset:3072
	v_add_u32_e32 v0, s54, v155
	ds_read_b128 v[176:179], v0
	ds_read_b128 v[188:191], v0 offset:1024
	ds_read_b128 v[192:195], v0 offset:2048
	ds_read_b128 v[196:199], v0 offset:3072
	s_add_u32 s24, s24, 0x40000
	s_addc_u32 s25, s25, 0
	s_mov_b32 m0, s74
	v_lshl_add_u64 v[218:219], s[24:25], 0, v[146:147]
	ds_read_b128 v[200:203], v186 offset:32768
	ds_read_b128 v[204:207], v186 offset:33792
	ds_read_b128 v[226:229], v186 offset:34816
	ds_read_b128 v[230:233], v186 offset:35840
	ds_read_b128 v[234:237], v186 offset:36864
	ds_read_b128 v[238:241], v186 offset:37888
	ds_read_b128 v[242:245], v186 offset:38912
	ds_read_b128 v[246:249], v186 offset:39936
	global_load_lds_dwordx4 v[218:219], off
	v_lshl_add_u64 v[218:219], s[24:25], 0, v[148:149]
	s_mov_b32 m0, s75
	s_nop 0
	global_load_lds_dwordx4 v[218:219], off
	s_waitcnt vmcnt(8)
	s_waitcnt lgkmcnt(0)
	s_barrier
	s_setprio 1
	s_waitcnt lgkmcnt(0)
	v_mfma_f32_16x16x32_bf16 v[142:145], v[58:61], v[200:203], v[142:145]
	v_mfma_f32_16x16x32_bf16 v[138:141], v[66:69], v[200:203], v[138:141]
	v_mfma_f32_16x16x32_bf16 v[126:129], v[58:61], v[226:229], v[126:129]
	v_mfma_f32_16x16x32_bf16 v[122:125], v[66:69], v[226:229], v[122:125]
	v_mfma_f32_16x16x32_bf16 v[110:113], v[58:61], v[234:237], v[110:113]
	v_mfma_f32_16x16x32_bf16 v[106:109], v[66:69], v[234:237], v[106:109]
	v_mfma_f32_16x16x32_bf16 v[94:97], v[58:61], v[242:245], v[94:97]
	v_mfma_f32_16x16x32_bf16 v[90:93], v[66:69], v[242:245], v[90:93]
	v_mfma_f32_16x16x32_bf16 v[142:145], v[62:65], v[204:207], v[142:145]
	v_mfma_f32_16x16x32_bf16 v[138:141], v[70:73], v[204:207], v[138:141]
	v_mfma_f32_16x16x32_bf16 v[126:129], v[62:65], v[230:233], v[126:129]
	v_mfma_f32_16x16x32_bf16 v[122:125], v[70:73], v[230:233], v[122:125]
	v_mfma_f32_16x16x32_bf16 v[110:113], v[62:65], v[238:241], v[110:113]
	v_mfma_f32_16x16x32_bf16 v[106:109], v[70:73], v[238:241], v[106:109]
	v_mfma_f32_16x16x32_bf16 v[94:97], v[62:65], v[246:249], v[94:97]
	v_mfma_f32_16x16x32_bf16 v[90:93], v[70:73], v[246:249], v[90:93]
	s_setprio 0
	s_setprio 1
	v_mfma_f32_16x16x32_bf16 v[134:137], v[176:179], v[200:203], v[134:137]
	v_mfma_f32_16x16x32_bf16 v[130:133], v[192:195], v[200:203], v[130:133]
	v_mfma_f32_16x16x32_bf16 v[118:121], v[176:179], v[226:229], v[118:121]
	v_mfma_f32_16x16x32_bf16 v[114:117], v[192:195], v[226:229], v[114:117]
	v_mfma_f32_16x16x32_bf16 v[102:105], v[176:179], v[234:237], v[102:105]
	v_mfma_f32_16x16x32_bf16 v[98:101], v[192:195], v[234:237], v[98:101]
	v_mfma_f32_16x16x32_bf16 v[86:89], v[176:179], v[242:245], v[86:89]
	v_mfma_f32_16x16x32_bf16 v[82:85], v[192:195], v[242:245], v[82:85]
	v_mfma_f32_16x16x32_bf16 v[134:137], v[188:191], v[204:207], v[134:137]
	v_mfma_f32_16x16x32_bf16 v[130:133], v[196:199], v[204:207], v[130:133]
	v_mfma_f32_16x16x32_bf16 v[118:121], v[188:191], v[230:233], v[118:121]
	v_mfma_f32_16x16x32_bf16 v[114:117], v[196:199], v[230:233], v[114:117]
	v_mfma_f32_16x16x32_bf16 v[102:105], v[188:191], v[238:241], v[102:105]
	v_mfma_f32_16x16x32_bf16 v[98:101], v[196:199], v[238:241], v[98:101]
	v_mfma_f32_16x16x32_bf16 v[86:89], v[188:191], v[246:249], v[86:89]
	v_mfma_f32_16x16x32_bf16 v[82:85], v[196:199], v[246:249], v[82:85]
	s_setprio 0
	s_barrier
	s_add_i32 s24, s47, s42
	v_lshl_add_u64 v[180:181], v[180:181], 0, s[44:45]
	s_mov_b32 m0, s24
	ds_read_b128 v[200:203], v186 offset:49152
	ds_read_b128 v[204:207], v186 offset:50176
	ds_read_b128 v[226:229], v186 offset:51200
	ds_read_b128 v[230:233], v186 offset:52224
	ds_read_b128 v[234:237], v186 offset:53248
	ds_read_b128 v[238:241], v186 offset:54272
	ds_read_b128 v[242:245], v186 offset:55296
	ds_read_b128 v[246:249], v186 offset:56320
	global_load_lds_dwordx4 v[180:181], off
	s_add_i32 m0, s24, 0x2000
	s_add_u32 s2, s2, 0x40080
	v_lshl_add_u64 v[180:181], v[222:223], 0, s[44:45]
	s_addc_u32 s3, s3, 0
	s_add_i32 s24, s54, s42
	global_load_lds_dwordx4 v[180:181], off
	v_lshl_add_u64 v[180:181], s[2:3], 0, v[146:147]
	s_mov_b32 m0, s24
	s_nop 0
	global_load_lds_dwordx4 v[180:181], off
	v_lshl_add_u64 v[180:181], s[2:3], 0, v[148:149]
	s_add_i32 m0, s24, 0x2000
	s_nop 0
	global_load_lds_dwordx4 v[180:181], off
	v_lshl_add_u64 v[180:181], v[224:225], 0, s[44:45]
	s_mov_b32 m0, s20
	s_nop 0
	global_load_lds_dwordx4 v[180:181], off
	v_lshl_add_u64 v[180:181], v[250:251], 0, s[44:45]
	s_mov_b32 m0, s21
	s_nop 0
	global_load_lds_dwordx4 v[180:181], off
	s_waitcnt vmcnt(8)
	s_waitcnt lgkmcnt(0)
	s_barrier
	s_setprio 1
	s_waitcnt lgkmcnt(0)
	v_mfma_f32_16x16x32_bf16 v[78:81], v[58:61], v[200:203], v[78:81]
	v_mfma_f32_16x16x32_bf16 v[74:77], v[66:69], v[200:203], v[74:77]
	v_mfma_f32_16x16x32_bf16 v[46:49], v[58:61], v[226:229], v[46:49]
	v_mfma_f32_16x16x32_bf16 v[42:45], v[66:69], v[226:229], v[42:45]
	v_mfma_f32_16x16x32_bf16 v[30:33], v[58:61], v[234:237], v[30:33]
	v_mfma_f32_16x16x32_bf16 v[26:29], v[66:69], v[234:237], v[26:29]
	v_mfma_f32_16x16x32_bf16 v[14:17], v[58:61], v[242:245], v[14:17]
	v_mfma_f32_16x16x32_bf16 v[10:13], v[66:69], v[242:245], v[10:13]
	v_mfma_f32_16x16x32_bf16 v[78:81], v[62:65], v[204:207], v[78:81]
	v_mfma_f32_16x16x32_bf16 v[74:77], v[70:73], v[204:207], v[74:77]
	v_mfma_f32_16x16x32_bf16 v[46:49], v[62:65], v[230:233], v[46:49]
	v_mfma_f32_16x16x32_bf16 v[42:45], v[70:73], v[230:233], v[42:45]
	v_mfma_f32_16x16x32_bf16 v[30:33], v[62:65], v[238:241], v[30:33]
	v_mfma_f32_16x16x32_bf16 v[26:29], v[70:73], v[238:241], v[26:29]
	v_mfma_f32_16x16x32_bf16 v[14:17], v[62:65], v[246:249], v[14:17]
	v_mfma_f32_16x16x32_bf16 v[10:13], v[70:73], v[246:249], v[10:13]
	s_setprio 0
	s_setprio 1
	v_mfma_f32_16x16x32_bf16 v[50:53], v[176:179], v[200:203], v[50:53]
	v_mfma_f32_16x16x32_bf16 v[70:73], v[188:191], v[204:207], v[50:53]
	v_mfma_f32_16x16x32_bf16 v[50:53], v[192:195], v[200:203], v[54:57]
	v_mfma_f32_16x16x32_bf16 v[38:41], v[176:179], v[226:229], v[38:41]
	v_mfma_f32_16x16x32_bf16 v[34:37], v[192:195], v[226:229], v[34:37]
	v_mfma_f32_16x16x32_bf16 v[22:25], v[176:179], v[234:237], v[22:25]
	v_mfma_f32_16x16x32_bf16 v[18:21], v[192:195], v[234:237], v[18:21]
	v_mfma_f32_16x16x32_bf16 v[6:9], v[176:179], v[242:245], v[6:9]
	v_mfma_f32_16x16x32_bf16 v[2:5], v[192:195], v[242:245], v[2:5]
	v_mfma_f32_16x16x32_bf16 v[66:69], v[196:199], v[204:207], v[50:53]
	v_mfma_f32_16x16x32_bf16 v[38:41], v[188:191], v[230:233], v[38:41]
	v_mfma_f32_16x16x32_bf16 v[34:37], v[196:199], v[230:233], v[34:37]
	v_mfma_f32_16x16x32_bf16 v[22:25], v[188:191], v[238:241], v[22:25]
	v_mfma_f32_16x16x32_bf16 v[18:21], v[196:199], v[238:241], v[18:21]
	v_mfma_f32_16x16x32_bf16 v[6:9], v[188:191], v[246:249], v[6:9]
	v_mfma_f32_16x16x32_bf16 v[2:5], v[196:199], v[246:249], v[2:5]
	s_add_i32 s46, s46, 2
	s_add_u32 s14, s14, 0x100
	s_addc_u32 s15, s15, 0
	s_add_u32 s31, s31, 0x100
	s_addc_u32 s33, s33, 0
	s_cmp_gt_u32 s46, 13
	s_setprio 0
	s_barrier
	s_cbranch_scc0 .LBB0_176
	s_and_b64 vcc, exec, s[22:23]
	s_cbranch_vccz .LBB0_179
	s_barrier

.LBB0_650:
	s_add_u32 s2, s4, 0x100
	s_addc_u32 s3, s5, 0
	s_add_i32 s49, 0, 0x10000
	s_cmp_eq_u32 s48, 12
	s_cselect_b32 s29, s17, s3
	s_cselect_b32 s28, s25, s2
	v_add_u32_e32 v0, s49, v135
	s_cselect_b32 s27, s15, s47
	s_cselect_b32 s26, s42, s46
	s_add_i32 s50, 0, 0x14000
	ds_read_b128 v[146:149], v0
	ds_read_b128 v[150:153], v0 offset:1024
	ds_read_b128 v[154:157], v0 offset:2048
	ds_read_b128 v[158:161], v0 offset:3072
	v_add_u32_e32 v0, s50, v135
	ds_read_b128 v[162:165], v0
	ds_read_b128 v[166:169], v0 offset:1024
	ds_read_b128 v[170:173], v0 offset:2048
	ds_read_b128 v[174:177], v0 offset:3072
	v_lshl_add_u64 v[142:143], s[4:5], 0, v[138:139]
	s_add_i32 m0, s23, 0xc000
	ds_read_b128 v[178:181], v144
	ds_read_b128 v[182:185], v144 offset:1024
	ds_read_b128 v[186:189], v144 offset:2048
	ds_read_b128 v[190:193], v144 offset:3072
	ds_read_b128 v[194:197], v144 offset:4096
	ds_read_b128 v[198:201], v144 offset:5120
	ds_read_b128 v[202:205], v144 offset:6144
	ds_read_b128 v[222:225], v144 offset:7168
	global_load_lds_dwordx4 v[142:143], off
	v_lshl_add_u64 v[142:143], s[4:5], 0, v[140:141]
	s_add_i32 m0, s23, 0xe000
	s_nop 0
	global_load_lds_dwordx4 v[142:143], off
	s_waitcnt vmcnt(8)
	s_waitcnt lgkmcnt(0)
	s_barrier
	s_setprio 1
	s_waitcnt lgkmcnt(0)
	v_mfma_f32_16x16x32_bf16 v[126:129], v[146:149], v[178:181], v[126:129]
	v_mfma_f32_16x16x32_bf16 v[122:125], v[154:157], v[178:181], v[122:125]
	v_mfma_f32_16x16x32_bf16 v[110:113], v[146:149], v[186:189], v[110:113]
	v_mfma_f32_16x16x32_bf16 v[106:109], v[154:157], v[186:189], v[106:109]
	v_mfma_f32_16x16x32_bf16 v[94:97], v[146:149], v[194:197], v[94:97]
	v_mfma_f32_16x16x32_bf16 v[90:93], v[154:157], v[194:197], v[90:93]
	v_mfma_f32_16x16x32_bf16 v[78:81], v[146:149], v[202:205], v[78:81]
	v_mfma_f32_16x16x32_bf16 v[74:77], v[154:157], v[202:205], v[74:77]
	v_mfma_f32_16x16x32_bf16 v[126:129], v[150:153], v[182:185], v[126:129]
	v_mfma_f32_16x16x32_bf16 v[122:125], v[158:161], v[182:185], v[122:125]
	v_mfma_f32_16x16x32_bf16 v[110:113], v[150:153], v[190:193], v[110:113]
	v_mfma_f32_16x16x32_bf16 v[106:109], v[158:161], v[190:193], v[106:109]
	v_mfma_f32_16x16x32_bf16 v[94:97], v[150:153], v[198:201], v[94:97]
	v_mfma_f32_16x16x32_bf16 v[90:93], v[158:161], v[198:201], v[90:93]
	v_mfma_f32_16x16x32_bf16 v[78:81], v[150:153], v[222:225], v[78:81]
	v_mfma_f32_16x16x32_bf16 v[74:77], v[158:161], v[222:225], v[74:77]
	s_setprio 0
	s_setprio 1
	v_mfma_f32_16x16x32_bf16 v[118:121], v[162:165], v[178:181], v[118:121]
	v_mfma_f32_16x16x32_bf16 v[114:117], v[170:173], v[178:181], v[114:117]
	v_mfma_f32_16x16x32_bf16 v[102:105], v[162:165], v[186:189], v[102:105]
	v_mfma_f32_16x16x32_bf16 v[98:101], v[170:173], v[186:189], v[98:101]
	v_mfma_f32_16x16x32_bf16 v[86:89], v[162:165], v[194:197], v[86:89]
	v_mfma_f32_16x16x32_bf16 v[82:85], v[170:173], v[194:197], v[82:85]
	v_mfma_f32_16x16x32_bf16 v[70:73], v[162:165], v[202:205], v[70:73]
	v_mfma_f32_16x16x32_bf16 v[66:69], v[170:173], v[202:205], v[66:69]
	v_mfma_f32_16x16x32_bf16 v[118:121], v[166:169], v[182:185], v[118:121]
	v_mfma_f32_16x16x32_bf16 v[114:117], v[174:177], v[182:185], v[114:117]
	v_mfma_f32_16x16x32_bf16 v[102:105], v[166:169], v[190:193], v[102:105]
	v_mfma_f32_16x16x32_bf16 v[98:101], v[174:177], v[190:193], v[98:101]
	v_mfma_f32_16x16x32_bf16 v[86:89], v[166:169], v[198:201], v[86:89]
	v_mfma_f32_16x16x32_bf16 v[82:85], v[174:177], v[198:201], v[82:85]
	v_mfma_f32_16x16x32_bf16 v[70:73], v[166:169], v[222:225], v[70:73]
	v_mfma_f32_16x16x32_bf16 v[66:69], v[174:177], v[222:225], v[66:69]
	s_setprio 0
	s_barrier
	s_add_i32 s4, s49, s30
	v_lshl_add_u64 v[142:143], s[26:27], 0, v[130:131]
	s_mov_b32 m0, s4
	ds_read_b128 v[178:181], v144 offset:16384
	ds_read_b128 v[182:185], v144 offset:17408
	ds_read_b128 v[186:189], v144 offset:18432
	ds_read_b128 v[190:193], v144 offset:19456
	ds_read_b128 v[194:197], v144 offset:20480
	ds_read_b128 v[198:201], v144 offset:21504
	ds_read_b128 v[202:205], v144 offset:22528
	ds_read_b128 v[222:225], v144 offset:23552
	global_load_lds_dwordx4 v[142:143], off
	s_add_i32 m0, s4, 0x2000
	s_add_u32 s4, s26, 0x40000
	v_lshl_add_u64 v[206:207], s[26:27], 0, v[132:133]
	s_addc_u32 s5, s27, 0
	s_add_i32 s49, s50, s30
	global_load_lds_dwordx4 v[206:207], off
	v_lshl_add_u64 v[218:219], s[4:5], 0, v[130:131]
	s_mov_b32 m0, s49
	v_lshl_add_u64 v[226:227], s[28:29], 0, v[132:133]
	global_load_lds_dwordx4 v[218:219], off
	v_lshl_add_u64 v[218:219], s[4:5], 0, v[132:133]
	s_add_i32 m0, s49, 0x2000
	s_nop 0
	global_load_lds_dwordx4 v[218:219], off
	v_lshl_add_u64 v[218:219], s[28:29], 0, v[130:131]
	s_mov_b32 m0, s23
	s_nop 0
	global_load_lds_dwordx4 v[218:219], off
	s_mov_b32 m0, s31
	s_nop 0
	global_load_lds_dwordx4 v[226:227], off
	s_waitcnt vmcnt(8)
	s_waitcnt lgkmcnt(0)
	s_barrier
	s_setprio 1
	s_waitcnt lgkmcnt(0)
	v_mfma_f32_16x16x32_bf16 v[62:65], v[146:149], v[178:181], v[62:65]
	v_mfma_f32_16x16x32_bf16 v[58:61], v[154:157], v[178:181], v[58:61]
	v_mfma_f32_16x16x32_bf16 v[46:49], v[146:149], v[186:189], v[46:49]
	v_mfma_f32_16x16x32_bf16 v[42:45], v[154:157], v[186:189], v[42:45]
	v_mfma_f32_16x16x32_bf16 v[30:33], v[146:149], v[194:197], v[30:33]
	v_mfma_f32_16x16x32_bf16 v[26:29], v[154:157], v[194:197], v[26:29]
	v_mfma_f32_16x16x32_bf16 v[14:17], v[146:149], v[202:205], v[14:17]
	v_mfma_f32_16x16x32_bf16 v[10:13], v[154:157], v[202:205], v[10:13]
	v_mfma_f32_16x16x32_bf16 v[62:65], v[150:153], v[182:185], v[62:65]
	v_mfma_f32_16x16x32_bf16 v[58:61], v[158:161], v[182:185], v[58:61]
	v_mfma_f32_16x16x32_bf16 v[46:49], v[150:153], v[190:193], v[46:49]
	v_mfma_f32_16x16x32_bf16 v[42:45], v[158:161], v[190:193], v[42:45]
	v_mfma_f32_16x16x32_bf16 v[30:33], v[150:153], v[198:201], v[30:33]
	v_mfma_f32_16x16x32_bf16 v[26:29], v[158:161], v[198:201], v[26:29]
	v_mfma_f32_16x16x32_bf16 v[14:17], v[150:153], v[222:225], v[14:17]
	v_mfma_f32_16x16x32_bf16 v[10:13], v[158:161], v[222:225], v[10:13]
	s_setprio 0
	s_setprio 1
	v_mfma_f32_16x16x32_bf16 v[54:57], v[162:165], v[178:181], v[54:57]
	v_mfma_f32_16x16x32_bf16 v[50:53], v[170:173], v[178:181], v[50:53]
	v_mfma_f32_16x16x32_bf16 v[38:41], v[162:165], v[186:189], v[38:41]
	v_mfma_f32_16x16x32_bf16 v[34:37], v[170:173], v[186:189], v[34:37]
	v_mfma_f32_16x16x32_bf16 v[22:25], v[162:165], v[194:197], v[22:25]
	v_mfma_f32_16x16x32_bf16 v[18:21], v[170:173], v[194:197], v[18:21]
	v_mfma_f32_16x16x32_bf16 v[6:9], v[162:165], v[202:205], v[6:9]
	v_mfma_f32_16x16x32_bf16 v[2:5], v[170:173], v[202:205], v[2:5]
	v_mfma_f32_16x16x32_bf16 v[54:57], v[166:169], v[182:185], v[54:57]
	v_mfma_f32_16x16x32_bf16 v[50:53], v[174:177], v[182:185], v[50:53]
	v_mfma_f32_16x16x32_bf16 v[38:41], v[166:169], v[190:193], v[38:41]
	v_mfma_f32_16x16x32_bf16 v[34:37], v[174:177], v[190:193], v[34:37]
	v_mfma_f32_16x16x32_bf16 v[22:25], v[166:169], v[198:201], v[22:25]
	v_mfma_f32_16x16x32_bf16 v[18:21], v[174:177], v[198:201], v[18:21]
	v_mfma_f32_16x16x32_bf16 v[6:9], v[166:169], v[222:225], v[6:9]
	v_mfma_f32_16x16x32_bf16 v[2:5], v[174:177], v[222:225], v[2:5]
	s_setprio 0
	s_barrier
	s_add_i32 s49, 0, 0x18000
	v_add_u32_e32 v0, s49, v135
	s_add_i32 s50, 0, 0x1c000
	ds_read_b128 v[146:149], v0
	ds_read_b128 v[150:153], v0 offset:1024
	ds_read_b128 v[154:157], v0 offset:2048
	ds_read_b128 v[158:161], v0 offset:3072
	v_add_u32_e32 v0, s50, v135
	ds_read_b128 v[162:165], v0
	ds_read_b128 v[166:169], v0 offset:1024
	ds_read_b128 v[170:173], v0 offset:2048
	ds_read_b128 v[174:177], v0 offset:3072
	s_add_u32 s4, s28, 0x40000
	s_addc_u32 s5, s29, 0
	s_mov_b32 m0, s33
	v_lshl_add_u64 v[228:229], s[4:5], 0, v[130:131]
	ds_read_b128 v[178:181], v144 offset:32768
	ds_read_b128 v[182:185], v144 offset:33792
	ds_read_b128 v[186:189], v144 offset:34816
	ds_read_b128 v[190:193], v144 offset:35840
	ds_read_b128 v[194:197], v144 offset:36864
	ds_read_b128 v[198:201], v144 offset:37888
	ds_read_b128 v[202:205], v144 offset:38912
	ds_read_b128 v[222:225], v144 offset:39936
	global_load_lds_dwordx4 v[228:229], off
	v_lshl_add_u64 v[228:229], s[4:5], 0, v[132:133]
	s_mov_b32 m0, s34
	s_nop 0
	global_load_lds_dwordx4 v[228:229], off
	s_waitcnt vmcnt(8)
	s_waitcnt lgkmcnt(0)
	s_barrier
	s_setprio 1
	s_waitcnt lgkmcnt(0)
	v_mfma_f32_16x16x32_bf16 v[126:129], v[146:149], v[178:181], v[126:129]
	v_mfma_f32_16x16x32_bf16 v[122:125], v[154:157], v[178:181], v[122:125]
	v_mfma_f32_16x16x32_bf16 v[110:113], v[146:149], v[186:189], v[110:113]
	v_mfma_f32_16x16x32_bf16 v[106:109], v[154:157], v[186:189], v[106:109]
	v_mfma_f32_16x16x32_bf16 v[94:97], v[146:149], v[194:197], v[94:97]
	v_mfma_f32_16x16x32_bf16 v[90:93], v[154:157], v[194:197], v[90:93]
	v_mfma_f32_16x16x32_bf16 v[78:81], v[146:149], v[202:205], v[78:81]
	v_mfma_f32_16x16x32_bf16 v[74:77], v[154:157], v[202:205], v[74:77]
	v_mfma_f32_16x16x32_bf16 v[126:129], v[150:153], v[182:185], v[126:129]
	v_mfma_f32_16x16x32_bf16 v[122:125], v[158:161], v[182:185], v[122:125]
	v_mfma_f32_16x16x32_bf16 v[110:113], v[150:153], v[190:193], v[110:113]
	v_mfma_f32_16x16x32_bf16 v[106:109], v[158:161], v[190:193], v[106:109]
	v_mfma_f32_16x16x32_bf16 v[94:97], v[150:153], v[198:201], v[94:97]
	v_mfma_f32_16x16x32_bf16 v[90:93], v[158:161], v[198:201], v[90:93]
	v_mfma_f32_16x16x32_bf16 v[78:81], v[150:153], v[222:225], v[78:81]
	v_mfma_f32_16x16x32_bf16 v[74:77], v[158:161], v[222:225], v[74:77]
	s_setprio 0
	s_setprio 1
	v_mfma_f32_16x16x32_bf16 v[118:121], v[162:165], v[178:181], v[118:121]
	v_mfma_f32_16x16x32_bf16 v[114:117], v[170:173], v[178:181], v[114:117]
	v_mfma_f32_16x16x32_bf16 v[102:105], v[162:165], v[186:189], v[102:105]
	v_mfma_f32_16x16x32_bf16 v[98:101], v[170:173], v[186:189], v[98:101]
	v_mfma_f32_16x16x32_bf16 v[86:89], v[162:165], v[194:197], v[86:89]
	v_mfma_f32_16x16x32_bf16 v[82:85], v[170:173], v[194:197], v[82:85]
	v_mfma_f32_16x16x32_bf16 v[70:73], v[162:165], v[202:205], v[70:73]
	v_mfma_f32_16x16x32_bf16 v[66:69], v[170:173], v[202:205], v[66:69]
	v_mfma_f32_16x16x32_bf16 v[118:121], v[166:169], v[182:185], v[118:121]
	v_mfma_f32_16x16x32_bf16 v[114:117], v[174:177], v[182:185], v[114:117]
	v_mfma_f32_16x16x32_bf16 v[102:105], v[166:169], v[190:193], v[102:105]
	v_mfma_f32_16x16x32_bf16 v[98:101], v[174:177], v[190:193], v[98:101]
	v_mfma_f32_16x16x32_bf16 v[86:89], v[166:169], v[198:201], v[86:89]
	v_mfma_f32_16x16x32_bf16 v[82:85], v[174:177], v[198:201], v[82:85]
	v_mfma_f32_16x16x32_bf16 v[70:73], v[166:169], v[222:225], v[70:73]
	v_mfma_f32_16x16x32_bf16 v[66:69], v[174:177], v[222:225], v[66:69]
	s_setprio 0
	s_barrier
	s_add_i32 s4, s49, s30
	v_lshl_add_u64 v[142:143], v[142:143], 0, s[44:45]
	s_mov_b32 m0, s4
	ds_read_b128 v[178:181], v144 offset:49152
	ds_read_b128 v[182:185], v144 offset:50176
	ds_read_b128 v[186:189], v144 offset:51200
	ds_read_b128 v[190:193], v144 offset:52224
	ds_read_b128 v[194:197], v144 offset:53248
	ds_read_b128 v[198:201], v144 offset:54272
	ds_read_b128 v[202:205], v144 offset:55296
	ds_read_b128 v[222:225], v144 offset:56320
	global_load_lds_dwordx4 v[142:143], off
	s_add_i32 m0, s4, 0x2000
	s_add_u32 s4, s26, 0x40080
	v_lshl_add_u64 v[142:143], v[206:207], 0, s[44:45]
	s_addc_u32 s5, s27, 0
	s_add_i32 s26, s50, s30
	global_load_lds_dwordx4 v[142:143], off
	v_lshl_add_u64 v[142:143], s[4:5], 0, v[130:131]
	s_mov_b32 m0, s26
	s_nop 0
	global_load_lds_dwordx4 v[142:143], off
	v_lshl_add_u64 v[142:143], s[4:5], 0, v[132:133]
	s_add_i32 m0, s26, 0x2000
	s_nop 0
	global_load_lds_dwordx4 v[142:143], off
	v_lshl_add_u64 v[142:143], v[218:219], 0, s[44:45]
	s_mov_b32 m0, s37
	s_nop 0
	global_load_lds_dwordx4 v[142:143], off
	v_lshl_add_u64 v[142:143], v[226:227], 0, s[44:45]
	s_mov_b32 m0, s38
	s_nop 0
	global_load_lds_dwordx4 v[142:143], off
	s_waitcnt vmcnt(8)
	s_waitcnt lgkmcnt(0)
	s_barrier
	s_setprio 1
	s_waitcnt lgkmcnt(0)
	v_mfma_f32_16x16x32_bf16 v[62:65], v[146:149], v[178:181], v[62:65]
	v_mfma_f32_16x16x32_bf16 v[58:61], v[154:157], v[178:181], v[58:61]
	v_mfma_f32_16x16x32_bf16 v[46:49], v[146:149], v[186:189], v[46:49]
	v_mfma_f32_16x16x32_bf16 v[42:45], v[154:157], v[186:189], v[42:45]
	v_mfma_f32_16x16x32_bf16 v[30:33], v[146:149], v[194:197], v[30:33]
	v_mfma_f32_16x16x32_bf16 v[26:29], v[154:157], v[194:197], v[26:29]
	v_mfma_f32_16x16x32_bf16 v[14:17], v[146:149], v[202:205], v[14:17]
	v_mfma_f32_16x16x32_bf16 v[10:13], v[154:157], v[202:205], v[10:13]
	v_mfma_f32_16x16x32_bf16 v[62:65], v[150:153], v[182:185], v[62:65]
	v_mfma_f32_16x16x32_bf16 v[58:61], v[158:161], v[182:185], v[58:61]
	v_mfma_f32_16x16x32_bf16 v[46:49], v[150:153], v[190:193], v[46:49]
	v_mfma_f32_16x16x32_bf16 v[42:45], v[158:161], v[190:193], v[42:45]
	v_mfma_f32_16x16x32_bf16 v[30:33], v[150:153], v[198:201], v[30:33]
	v_mfma_f32_16x16x32_bf16 v[26:29], v[158:161], v[198:201], v[26:29]
	v_mfma_f32_16x16x32_bf16 v[14:17], v[150:153], v[222:225], v[14:17]
	v_mfma_f32_16x16x32_bf16 v[10:13], v[158:161], v[222:225], v[10:13]
	s_setprio 0
	s_setprio 1
	v_mfma_f32_16x16x32_bf16 v[54:57], v[162:165], v[178:181], v[54:57]
	v_mfma_f32_16x16x32_bf16 v[50:53], v[170:173], v[178:181], v[50:53]
	v_mfma_f32_16x16x32_bf16 v[38:41], v[162:165], v[186:189], v[38:41]
	v_mfma_f32_16x16x32_bf16 v[34:37], v[170:173], v[186:189], v[34:37]
	v_mfma_f32_16x16x32_bf16 v[22:25], v[162:165], v[194:197], v[22:25]
	v_mfma_f32_16x16x32_bf16 v[18:21], v[170:173], v[194:197], v[18:21]
	v_mfma_f32_16x16x32_bf16 v[6:9], v[162:165], v[202:205], v[6:9]
	v_mfma_f32_16x16x32_bf16 v[2:5], v[170:173], v[202:205], v[2:5]
	v_mfma_f32_16x16x32_bf16 v[54:57], v[166:169], v[182:185], v[54:57]
	v_mfma_f32_16x16x32_bf16 v[50:53], v[174:177], v[182:185], v[50:53]
	v_mfma_f32_16x16x32_bf16 v[38:41], v[166:169], v[190:193], v[38:41]
	v_mfma_f32_16x16x32_bf16 v[34:37], v[174:177], v[190:193], v[34:37]
	v_mfma_f32_16x16x32_bf16 v[22:25], v[166:169], v[198:201], v[22:25]
	v_mfma_f32_16x16x32_bf16 v[18:21], v[174:177], v[198:201], v[18:21]
	v_mfma_f32_16x16x32_bf16 v[6:9], v[166:169], v[222:225], v[6:9]
	v_mfma_f32_16x16x32_bf16 v[2:5], v[174:177], v[222:225], v[2:5]
	s_add_i32 s48, s48, 2
	s_add_u32 s46, s46, 0x100
	s_addc_u32 s47, s47, 0
	s_mov_b64 s[4:5], s[2:3]
	s_cmp_gt_u32 s48, 13
	s_setprio 0
	s_barrier
	s_cbranch_scc0 .LBB0_650
	s_and_b64 vcc, exec, s[12:13]
	s_cbranch_vccz .LBB0_653
	s_barrier

.LBB0_783:
	s_add_u32 s2, s4, 0xfffc0080
	s_addc_u32 s3, s5, -1
	s_add_i32 s48, 0, 0x10000
	s_cmp_eq_u32 s47, 12
	s_cselect_b32 s27, s17, s3
	s_cselect_b32 s26, s25, s2
	s_cselect_b32 s3, s15, s46
	s_cselect_b32 s2, s41, s42
	s_add_i32 s50, 0, 0x14000
	v_add_u32_e32 v154, s48, v140
	v_add_u32_e32 v170, s50, v140
	ds_read_b128 v[142:145], v154
	ds_read_b128 v[146:149], v154 offset:1024
	ds_read_b128 v[150:153], v154 offset:2048
	ds_read_b128 v[154:157], v154 offset:3072
	ds_read_b128 v[158:161], v170
	ds_read_b128 v[162:165], v170 offset:1024
	ds_read_b128 v[166:169], v170 offset:2048
	ds_read_b128 v[170:173], v170 offset:3072
	v_lshl_add_u64 v[206:207], s[4:5], 0, v[136:137]
	s_add_i32 m0, s23, 0xc000
	ds_read_b128 v[174:177], v141
	ds_read_b128 v[178:181], v141 offset:1024
	ds_read_b128 v[182:185], v141 offset:2048
	ds_read_b128 v[186:189], v141 offset:3072
	ds_read_b128 v[190:193], v141 offset:4096
	ds_read_b128 v[194:197], v141 offset:5120
	ds_read_b128 v[198:201], v141 offset:6144
	ds_read_b128 v[202:205], v141 offset:7168
	global_load_lds_dwordx4 v[206:207], off
	v_lshl_add_u64 v[206:207], s[4:5], 0, v[138:139]
	s_add_i32 m0, s23, 0xe000
	s_nop 0
	global_load_lds_dwordx4 v[206:207], off
	s_waitcnt vmcnt(8)
	s_waitcnt lgkmcnt(0)
	s_barrier
	s_setprio 1
	s_waitcnt lgkmcnt(0)
	v_mfma_f32_16x16x32_bf16 v[122:125], v[142:145], v[174:177], v[122:125]
	v_mfma_f32_16x16x32_bf16 v[114:117], v[150:153], v[174:177], v[114:117]
	v_mfma_f32_16x16x32_bf16 v[106:109], v[142:145], v[182:185], v[106:109]
	v_mfma_f32_16x16x32_bf16 v[98:101], v[150:153], v[182:185], v[98:101]
	v_mfma_f32_16x16x32_bf16 v[90:93], v[142:145], v[190:193], v[90:93]
	v_mfma_f32_16x16x32_bf16 v[82:85], v[150:153], v[190:193], v[82:85]
	v_mfma_f32_16x16x32_bf16 v[74:77], v[142:145], v[198:201], v[74:77]
	v_mfma_f32_16x16x32_bf16 v[66:69], v[150:153], v[198:201], v[66:69]
	v_mfma_f32_16x16x32_bf16 v[122:125], v[146:149], v[178:181], v[122:125]
	v_mfma_f32_16x16x32_bf16 v[114:117], v[154:157], v[178:181], v[114:117]
	v_mfma_f32_16x16x32_bf16 v[106:109], v[146:149], v[186:189], v[106:109]
	v_mfma_f32_16x16x32_bf16 v[98:101], v[154:157], v[186:189], v[98:101]
	v_mfma_f32_16x16x32_bf16 v[90:93], v[146:149], v[194:197], v[90:93]
	v_mfma_f32_16x16x32_bf16 v[82:85], v[154:157], v[194:197], v[82:85]
	v_mfma_f32_16x16x32_bf16 v[74:77], v[146:149], v[202:205], v[74:77]
	v_mfma_f32_16x16x32_bf16 v[66:69], v[154:157], v[202:205], v[66:69]
	s_setprio 0
	s_setprio 1
	v_mfma_f32_16x16x32_bf16 v[126:129], v[158:161], v[174:177], v[126:129]
	v_mfma_f32_16x16x32_bf16 v[118:121], v[166:169], v[174:177], v[118:121]
	v_mfma_f32_16x16x32_bf16 v[110:113], v[158:161], v[182:185], v[110:113]
	v_mfma_f32_16x16x32_bf16 v[102:105], v[166:169], v[182:185], v[102:105]
	v_mfma_f32_16x16x32_bf16 v[94:97], v[158:161], v[190:193], v[94:97]
	v_mfma_f32_16x16x32_bf16 v[86:89], v[166:169], v[190:193], v[86:89]
	v_mfma_f32_16x16x32_bf16 v[78:81], v[158:161], v[198:201], v[78:81]
	v_mfma_f32_16x16x32_bf16 v[70:73], v[166:169], v[198:201], v[70:73]
	v_mfma_f32_16x16x32_bf16 v[126:129], v[162:165], v[178:181], v[126:129]
	v_mfma_f32_16x16x32_bf16 v[118:121], v[170:173], v[178:181], v[118:121]
	v_mfma_f32_16x16x32_bf16 v[110:113], v[162:165], v[186:189], v[110:113]
	v_mfma_f32_16x16x32_bf16 v[102:105], v[170:173], v[186:189], v[102:105]
	v_mfma_f32_16x16x32_bf16 v[94:97], v[162:165], v[194:197], v[94:97]
	v_mfma_f32_16x16x32_bf16 v[86:89], v[170:173], v[194:197], v[86:89]
	v_mfma_f32_16x16x32_bf16 v[78:81], v[162:165], v[202:205], v[78:81]
	v_mfma_f32_16x16x32_bf16 v[70:73], v[170:173], v[202:205], v[70:73]
	s_setprio 0
	s_barrier
	s_add_i32 s48, s48, s28
	v_lshl_add_u64 v[206:207], s[2:3], 0, v[132:133]
	s_mov_b32 m0, s48
	ds_read_b128 v[174:177], v141 offset:16384
	ds_read_b128 v[178:181], v141 offset:17408
	ds_read_b128 v[182:185], v141 offset:18432
	ds_read_b128 v[186:189], v141 offset:19456
	ds_read_b128 v[190:193], v141 offset:20480
	ds_read_b128 v[194:197], v141 offset:21504
	ds_read_b128 v[198:201], v141 offset:22528
	ds_read_b128 v[202:205], v141 offset:23552
	global_load_lds_dwordx4 v[206:207], off
	s_add_i32 m0, s48, 0x2000
	s_add_u32 s48, s2, 0x40000
	v_lshl_add_u64 v[218:219], s[2:3], 0, v[130:131]
	s_addc_u32 s49, s3, 0
	s_add_i32 s50, s50, s28
	global_load_lds_dwordx4 v[218:219], off
	v_lshl_add_u64 v[222:223], s[48:49], 0, v[132:133]
	s_mov_b32 m0, s50
	v_lshl_add_u64 v[224:225], s[26:27], 0, v[130:131]
	global_load_lds_dwordx4 v[222:223], off
	v_lshl_add_u64 v[222:223], s[48:49], 0, v[130:131]
	s_add_i32 m0, s50, 0x2000
	s_nop 0
	global_load_lds_dwordx4 v[222:223], off
	v_lshl_add_u64 v[222:223], s[26:27], 0, v[132:133]
	s_mov_b32 m0, s23
	s_nop 0
	global_load_lds_dwordx4 v[222:223], off
	s_mov_b32 m0, s31
	s_nop 0
	global_load_lds_dwordx4 v[224:225], off
	s_waitcnt vmcnt(8)
	s_waitcnt lgkmcnt(0)
	s_barrier
	s_setprio 1
	s_waitcnt lgkmcnt(0)
	v_mfma_f32_16x16x32_bf16 v[58:61], v[142:145], v[174:177], v[58:61]
	v_mfma_f32_16x16x32_bf16 v[50:53], v[150:153], v[174:177], v[50:53]
	v_mfma_f32_16x16x32_bf16 v[42:45], v[142:145], v[182:185], v[42:45]
	v_mfma_f32_16x16x32_bf16 v[34:37], v[150:153], v[182:185], v[34:37]
	v_mfma_f32_16x16x32_bf16 v[26:29], v[142:145], v[190:193], v[26:29]
	v_mfma_f32_16x16x32_bf16 v[18:21], v[150:153], v[190:193], v[18:21]
	v_mfma_f32_16x16x32_bf16 v[10:13], v[142:145], v[198:201], v[10:13]
	v_mfma_f32_16x16x32_bf16 v[2:5], v[150:153], v[198:201], v[2:5]
	v_mfma_f32_16x16x32_bf16 v[58:61], v[146:149], v[178:181], v[58:61]
	v_mfma_f32_16x16x32_bf16 v[50:53], v[154:157], v[178:181], v[50:53]
	v_mfma_f32_16x16x32_bf16 v[42:45], v[146:149], v[186:189], v[42:45]
	v_mfma_f32_16x16x32_bf16 v[34:37], v[154:157], v[186:189], v[34:37]
	v_mfma_f32_16x16x32_bf16 v[26:29], v[146:149], v[194:197], v[26:29]
	v_mfma_f32_16x16x32_bf16 v[18:21], v[154:157], v[194:197], v[18:21]
	v_mfma_f32_16x16x32_bf16 v[10:13], v[146:149], v[202:205], v[10:13]
	v_mfma_f32_16x16x32_bf16 v[2:5], v[154:157], v[202:205], v[2:5]
	s_setprio 0
	s_setprio 1
	v_mfma_f32_16x16x32_bf16 v[62:65], v[158:161], v[174:177], v[62:65]
	v_mfma_f32_16x16x32_bf16 v[54:57], v[166:169], v[174:177], v[54:57]
	v_mfma_f32_16x16x32_bf16 v[46:49], v[158:161], v[182:185], v[46:49]
	v_mfma_f32_16x16x32_bf16 v[38:41], v[166:169], v[182:185], v[38:41]
	v_mfma_f32_16x16x32_bf16 v[30:33], v[158:161], v[190:193], v[30:33]
	v_mfma_f32_16x16x32_bf16 v[22:25], v[166:169], v[190:193], v[22:25]
	v_mfma_f32_16x16x32_bf16 v[14:17], v[158:161], v[198:201], v[14:17]
	v_mfma_f32_16x16x32_bf16 v[6:9], v[166:169], v[198:201], v[6:9]
	v_mfma_f32_16x16x32_bf16 v[62:65], v[162:165], v[178:181], v[62:65]
	v_mfma_f32_16x16x32_bf16 v[54:57], v[170:173], v[178:181], v[54:57]
	v_mfma_f32_16x16x32_bf16 v[46:49], v[162:165], v[186:189], v[46:49]
	v_mfma_f32_16x16x32_bf16 v[38:41], v[170:173], v[186:189], v[38:41]
	v_mfma_f32_16x16x32_bf16 v[30:33], v[162:165], v[194:197], v[30:33]
	v_mfma_f32_16x16x32_bf16 v[22:25], v[170:173], v[194:197], v[22:25]
	v_mfma_f32_16x16x32_bf16 v[14:17], v[162:165], v[202:205], v[14:17]
	v_mfma_f32_16x16x32_bf16 v[6:9], v[170:173], v[202:205], v[6:9]
	s_setprio 0
	s_barrier
	s_add_i32 s48, 0, 0x18000
	s_add_i32 s49, 0, 0x1c000
	v_add_u32_e32 v154, s48, v140
	v_add_u32_e32 v170, s49, v140
	ds_read_b128 v[142:145], v154
	ds_read_b128 v[146:149], v154 offset:1024
	ds_read_b128 v[150:153], v154 offset:2048
	ds_read_b128 v[154:157], v154 offset:3072
	ds_read_b128 v[158:161], v170
	ds_read_b128 v[162:165], v170 offset:1024
	ds_read_b128 v[166:169], v170 offset:2048
	ds_read_b128 v[170:173], v170 offset:3072
	s_add_u32 s26, s26, 0x40000
	s_addc_u32 s27, s27, 0
	s_mov_b32 m0, s33
	v_lshl_add_u64 v[226:227], s[26:27], 0, v[132:133]
	ds_read_b128 v[174:177], v141 offset:32768
	ds_read_b128 v[178:181], v141 offset:33792
	ds_read_b128 v[182:185], v141 offset:34816
	ds_read_b128 v[186:189], v141 offset:35840
	ds_read_b128 v[190:193], v141 offset:36864
	ds_read_b128 v[194:197], v141 offset:37888
	ds_read_b128 v[198:201], v141 offset:38912
	ds_read_b128 v[202:205], v141 offset:39936
	global_load_lds_dwordx4 v[226:227], off
	v_lshl_add_u64 v[226:227], s[26:27], 0, v[130:131]
	s_mov_b32 m0, s34
	s_nop 0
	global_load_lds_dwordx4 v[226:227], off
	s_waitcnt vmcnt(8)
	s_waitcnt lgkmcnt(0)
	s_barrier
	s_setprio 1
	s_waitcnt lgkmcnt(0)
	v_mfma_f32_16x16x32_bf16 v[122:125], v[142:145], v[174:177], v[122:125]
	v_mfma_f32_16x16x32_bf16 v[114:117], v[150:153], v[174:177], v[114:117]
	v_mfma_f32_16x16x32_bf16 v[106:109], v[142:145], v[182:185], v[106:109]
	v_mfma_f32_16x16x32_bf16 v[98:101], v[150:153], v[182:185], v[98:101]
	v_mfma_f32_16x16x32_bf16 v[90:93], v[142:145], v[190:193], v[90:93]
	v_mfma_f32_16x16x32_bf16 v[82:85], v[150:153], v[190:193], v[82:85]
	v_mfma_f32_16x16x32_bf16 v[74:77], v[142:145], v[198:201], v[74:77]
	v_mfma_f32_16x16x32_bf16 v[66:69], v[150:153], v[198:201], v[66:69]
	v_mfma_f32_16x16x32_bf16 v[122:125], v[146:149], v[178:181], v[122:125]
	v_mfma_f32_16x16x32_bf16 v[114:117], v[154:157], v[178:181], v[114:117]
	v_mfma_f32_16x16x32_bf16 v[106:109], v[146:149], v[186:189], v[106:109]
	v_mfma_f32_16x16x32_bf16 v[98:101], v[154:157], v[186:189], v[98:101]
	v_mfma_f32_16x16x32_bf16 v[90:93], v[146:149], v[194:197], v[90:93]
	v_mfma_f32_16x16x32_bf16 v[82:85], v[154:157], v[194:197], v[82:85]
	v_mfma_f32_16x16x32_bf16 v[74:77], v[146:149], v[202:205], v[74:77]
	v_mfma_f32_16x16x32_bf16 v[66:69], v[154:157], v[202:205], v[66:69]
	s_setprio 0
	s_setprio 1
	v_mfma_f32_16x16x32_bf16 v[126:129], v[158:161], v[174:177], v[126:129]
	v_mfma_f32_16x16x32_bf16 v[118:121], v[166:169], v[174:177], v[118:121]
	v_mfma_f32_16x16x32_bf16 v[110:113], v[158:161], v[182:185], v[110:113]
	v_mfma_f32_16x16x32_bf16 v[102:105], v[166:169], v[182:185], v[102:105]
	v_mfma_f32_16x16x32_bf16 v[94:97], v[158:161], v[190:193], v[94:97]
	v_mfma_f32_16x16x32_bf16 v[86:89], v[166:169], v[190:193], v[86:89]
	v_mfma_f32_16x16x32_bf16 v[78:81], v[158:161], v[198:201], v[78:81]
	v_mfma_f32_16x16x32_bf16 v[70:73], v[166:169], v[198:201], v[70:73]
	v_mfma_f32_16x16x32_bf16 v[126:129], v[162:165], v[178:181], v[126:129]
	v_mfma_f32_16x16x32_bf16 v[118:121], v[170:173], v[178:181], v[118:121]
	v_mfma_f32_16x16x32_bf16 v[110:113], v[162:165], v[186:189], v[110:113]
	v_mfma_f32_16x16x32_bf16 v[102:105], v[170:173], v[186:189], v[102:105]
	v_mfma_f32_16x16x32_bf16 v[94:97], v[162:165], v[194:197], v[94:97]
	v_mfma_f32_16x16x32_bf16 v[86:89], v[170:173], v[194:197], v[86:89]
	v_mfma_f32_16x16x32_bf16 v[78:81], v[162:165], v[202:205], v[78:81]
	v_mfma_f32_16x16x32_bf16 v[70:73], v[170:173], v[202:205], v[70:73]
	s_setprio 0
	s_barrier
	s_add_i32 s26, s48, s28
	v_lshl_add_u64 v[206:207], v[206:207], 0, s[44:45]
	s_mov_b32 m0, s26
	ds_read_b128 v[174:177], v141 offset:49152
	ds_read_b128 v[178:181], v141 offset:50176
	ds_read_b128 v[182:185], v141 offset:51200
	ds_read_b128 v[186:189], v141 offset:52224
	ds_read_b128 v[190:193], v141 offset:53248
	ds_read_b128 v[194:197], v141 offset:54272
	ds_read_b128 v[198:201], v141 offset:55296
	ds_read_b128 v[202:205], v141 offset:56320
	global_load_lds_dwordx4 v[206:207], off
	s_add_i32 m0, s26, 0x2000
	s_add_u32 s2, s2, 0x40080
	v_lshl_add_u64 v[206:207], v[218:219], 0, s[44:45]
	s_addc_u32 s3, s3, 0
	s_add_i32 s26, s49, s28
	global_load_lds_dwordx4 v[206:207], off
	v_lshl_add_u64 v[206:207], s[2:3], 0, v[132:133]
	s_mov_b32 m0, s26
	s_nop 0
	global_load_lds_dwordx4 v[206:207], off
	v_lshl_add_u64 v[206:207], s[2:3], 0, v[130:131]
	s_add_i32 m0, s26, 0x2000
	s_nop 0
	global_load_lds_dwordx4 v[206:207], off
	v_lshl_add_u64 v[206:207], v[222:223], 0, s[44:45]
	s_mov_b32 m0, s35
	s_nop 0
	global_load_lds_dwordx4 v[206:207], off
	v_lshl_add_u64 v[206:207], v[224:225], 0, s[44:45]
	s_mov_b32 m0, s36
	s_nop 0
	global_load_lds_dwordx4 v[206:207], off
	s_waitcnt vmcnt(8)
	s_waitcnt lgkmcnt(0)
	s_barrier
	s_setprio 1
	s_waitcnt lgkmcnt(0)
	v_mfma_f32_16x16x32_bf16 v[58:61], v[142:145], v[174:177], v[58:61]
	v_mfma_f32_16x16x32_bf16 v[50:53], v[150:153], v[174:177], v[50:53]
	v_mfma_f32_16x16x32_bf16 v[42:45], v[142:145], v[182:185], v[42:45]
	v_mfma_f32_16x16x32_bf16 v[34:37], v[150:153], v[182:185], v[34:37]
	v_mfma_f32_16x16x32_bf16 v[26:29], v[142:145], v[190:193], v[26:29]
	v_mfma_f32_16x16x32_bf16 v[18:21], v[150:153], v[190:193], v[18:21]
	v_mfma_f32_16x16x32_bf16 v[10:13], v[142:145], v[198:201], v[10:13]
	v_mfma_f32_16x16x32_bf16 v[2:5], v[150:153], v[198:201], v[2:5]
	v_mfma_f32_16x16x32_bf16 v[58:61], v[146:149], v[178:181], v[58:61]
	v_mfma_f32_16x16x32_bf16 v[50:53], v[154:157], v[178:181], v[50:53]
	v_mfma_f32_16x16x32_bf16 v[42:45], v[146:149], v[186:189], v[42:45]
	v_mfma_f32_16x16x32_bf16 v[34:37], v[154:157], v[186:189], v[34:37]
	v_mfma_f32_16x16x32_bf16 v[26:29], v[146:149], v[194:197], v[26:29]
	v_mfma_f32_16x16x32_bf16 v[18:21], v[154:157], v[194:197], v[18:21]
	v_mfma_f32_16x16x32_bf16 v[10:13], v[146:149], v[202:205], v[10:13]
	v_mfma_f32_16x16x32_bf16 v[2:5], v[154:157], v[202:205], v[2:5]
	s_setprio 0
	s_setprio 1
	v_mfma_f32_16x16x32_bf16 v[62:65], v[158:161], v[174:177], v[62:65]
	v_mfma_f32_16x16x32_bf16 v[54:57], v[166:169], v[174:177], v[54:57]
	v_mfma_f32_16x16x32_bf16 v[46:49], v[158:161], v[182:185], v[46:49]
	v_mfma_f32_16x16x32_bf16 v[38:41], v[166:169], v[182:185], v[38:41]
	v_mfma_f32_16x16x32_bf16 v[30:33], v[158:161], v[190:193], v[30:33]
	v_mfma_f32_16x16x32_bf16 v[22:25], v[166:169], v[190:193], v[22:25]
	v_mfma_f32_16x16x32_bf16 v[14:17], v[158:161], v[198:201], v[14:17]
	v_mfma_f32_16x16x32_bf16 v[6:9], v[166:169], v[198:201], v[6:9]
	v_mfma_f32_16x16x32_bf16 v[62:65], v[162:165], v[178:181], v[62:65]
	v_mfma_f32_16x16x32_bf16 v[54:57], v[170:173], v[178:181], v[54:57]
	v_mfma_f32_16x16x32_bf16 v[46:49], v[162:165], v[186:189], v[46:49]
	v_mfma_f32_16x16x32_bf16 v[38:41], v[170:173], v[186:189], v[38:41]
	v_mfma_f32_16x16x32_bf16 v[30:33], v[162:165], v[194:197], v[30:33]
	v_mfma_f32_16x16x32_bf16 v[22:25], v[170:173], v[194:197], v[22:25]
	v_mfma_f32_16x16x32_bf16 v[14:17], v[162:165], v[202:205], v[14:17]
	v_mfma_f32_16x16x32_bf16 v[6:9], v[170:173], v[202:205], v[6:9]
	s_add_i32 s47, s47, 2
	s_add_u32 s4, s4, 0x100
	s_addc_u32 s5, s5, 0
	s_add_u32 s42, s42, 0x100
	s_addc_u32 s46, s46, 0
	s_cmp_gt_u32 s47, 13
	s_setprio 0
	s_barrier
	s_cbranch_scc0 .LBB0_783
	s_and_b64 vcc, exec, s[12:13]
	s_cbranch_vccz .LBB0_786
	s_barrier

.LBB0_849:
	s_add_u32 s2, s18, 0x100
	s_addc_u32 s3, s19, 0
	s_add_i32 s47, 0, 0x10000
	s_cmp_eq_u32 s46, 40
	s_cselect_b32 s23, s9, s3
	s_cselect_b32 s22, s8, s2
	v_add_u32_e32 v0, s47, v135
	s_cselect_b32 s21, s15, s42
	s_cselect_b32 s20, s14, s17
	s_add_i32 s48, 0, 0x14000
	ds_read_b128 v[146:149], v0
	ds_read_b128 v[150:153], v0 offset:1024
	ds_read_b128 v[154:157], v0 offset:2048
	ds_read_b128 v[158:161], v0 offset:3072
	v_add_u32_e32 v0, s48, v135
	ds_read_b128 v[162:165], v0
	ds_read_b128 v[166:169], v0 offset:1024
	ds_read_b128 v[170:173], v0 offset:2048
	ds_read_b128 v[174:177], v0 offset:3072
	v_lshl_add_u64 v[142:143], s[18:19], 0, v[138:139]
	s_add_i32 m0, s25, 0xc000
	ds_read_b128 v[178:181], v144
	ds_read_b128 v[182:185], v144 offset:1024
	ds_read_b128 v[186:189], v144 offset:2048
	ds_read_b128 v[190:193], v144 offset:3072
	ds_read_b128 v[194:197], v144 offset:4096
	ds_read_b128 v[198:201], v144 offset:5120
	ds_read_b128 v[202:205], v144 offset:6144
	ds_read_b128 v[222:225], v144 offset:7168
	global_load_lds_dwordx4 v[142:143], off
	v_lshl_add_u64 v[142:143], s[18:19], 0, v[140:141]
	s_add_i32 m0, s25, 0xe000
	s_nop 0
	global_load_lds_dwordx4 v[142:143], off
	s_waitcnt vmcnt(8)
	s_waitcnt lgkmcnt(0)
	s_barrier
	s_setprio 1
	s_waitcnt lgkmcnt(0)
	v_mfma_f32_16x16x32_bf16 v[126:129], v[146:149], v[178:181], v[126:129]
	v_mfma_f32_16x16x32_bf16 v[122:125], v[154:157], v[178:181], v[122:125]
	v_mfma_f32_16x16x32_bf16 v[110:113], v[146:149], v[186:189], v[110:113]
	v_mfma_f32_16x16x32_bf16 v[106:109], v[154:157], v[186:189], v[106:109]
	v_mfma_f32_16x16x32_bf16 v[94:97], v[146:149], v[194:197], v[94:97]
	v_mfma_f32_16x16x32_bf16 v[90:93], v[154:157], v[194:197], v[90:93]
	v_mfma_f32_16x16x32_bf16 v[78:81], v[146:149], v[202:205], v[78:81]
	v_mfma_f32_16x16x32_bf16 v[74:77], v[154:157], v[202:205], v[74:77]
	v_mfma_f32_16x16x32_bf16 v[126:129], v[150:153], v[182:185], v[126:129]
	v_mfma_f32_16x16x32_bf16 v[122:125], v[158:161], v[182:185], v[122:125]
	v_mfma_f32_16x16x32_bf16 v[110:113], v[150:153], v[190:193], v[110:113]
	v_mfma_f32_16x16x32_bf16 v[106:109], v[158:161], v[190:193], v[106:109]
	v_mfma_f32_16x16x32_bf16 v[94:97], v[150:153], v[198:201], v[94:97]
	v_mfma_f32_16x16x32_bf16 v[90:93], v[158:161], v[198:201], v[90:93]
	v_mfma_f32_16x16x32_bf16 v[78:81], v[150:153], v[222:225], v[78:81]
	v_mfma_f32_16x16x32_bf16 v[74:77], v[158:161], v[222:225], v[74:77]
	s_setprio 0
	s_setprio 1
	v_mfma_f32_16x16x32_bf16 v[118:121], v[162:165], v[178:181], v[118:121]
	v_mfma_f32_16x16x32_bf16 v[114:117], v[170:173], v[178:181], v[114:117]
	v_mfma_f32_16x16x32_bf16 v[102:105], v[162:165], v[186:189], v[102:105]
	v_mfma_f32_16x16x32_bf16 v[98:101], v[170:173], v[186:189], v[98:101]
	v_mfma_f32_16x16x32_bf16 v[86:89], v[162:165], v[194:197], v[86:89]
	v_mfma_f32_16x16x32_bf16 v[82:85], v[170:173], v[194:197], v[82:85]
	v_mfma_f32_16x16x32_bf16 v[70:73], v[162:165], v[202:205], v[70:73]
	v_mfma_f32_16x16x32_bf16 v[66:69], v[170:173], v[202:205], v[66:69]
	v_mfma_f32_16x16x32_bf16 v[118:121], v[166:169], v[182:185], v[118:121]
	v_mfma_f32_16x16x32_bf16 v[114:117], v[174:177], v[182:185], v[114:117]
	v_mfma_f32_16x16x32_bf16 v[102:105], v[166:169], v[190:193], v[102:105]
	v_mfma_f32_16x16x32_bf16 v[98:101], v[174:177], v[190:193], v[98:101]
	v_mfma_f32_16x16x32_bf16 v[86:89], v[166:169], v[198:201], v[86:89]
	v_mfma_f32_16x16x32_bf16 v[82:85], v[174:177], v[198:201], v[82:85]
	v_mfma_f32_16x16x32_bf16 v[70:73], v[166:169], v[222:225], v[70:73]
	v_mfma_f32_16x16x32_bf16 v[66:69], v[174:177], v[222:225], v[66:69]
	s_setprio 0
	s_barrier
	s_add_i32 s18, s47, s24
	v_lshl_add_u64 v[142:143], s[20:21], 0, v[130:131]
	s_mov_b32 m0, s18
	ds_read_b128 v[178:181], v144 offset:16384
	ds_read_b128 v[182:185], v144 offset:17408
	ds_read_b128 v[186:189], v144 offset:18432
	ds_read_b128 v[190:193], v144 offset:19456
	ds_read_b128 v[194:197], v144 offset:20480
	ds_read_b128 v[198:201], v144 offset:21504
	ds_read_b128 v[202:205], v144 offset:22528
	ds_read_b128 v[222:225], v144 offset:23552
	global_load_lds_dwordx4 v[142:143], off
	s_add_i32 m0, s18, 0x2000
	s_add_u32 s18, s20, 0xb0000
	v_lshl_add_u64 v[206:207], s[20:21], 0, v[132:133]
	s_addc_u32 s19, s21, 0
	s_add_i32 s47, s48, s24
	global_load_lds_dwordx4 v[206:207], off
	v_lshl_add_u64 v[218:219], s[18:19], 0, v[130:131]
	s_mov_b32 m0, s47
	v_lshl_add_u64 v[226:227], s[22:23], 0, v[132:133]
	global_load_lds_dwordx4 v[218:219], off
	v_lshl_add_u64 v[218:219], s[18:19], 0, v[132:133]
	s_add_i32 m0, s47, 0x2000
	s_nop 0
	global_load_lds_dwordx4 v[218:219], off
	v_lshl_add_u64 v[218:219], s[22:23], 0, v[130:131]
	s_mov_b32 m0, s25
	s_nop 0
	global_load_lds_dwordx4 v[218:219], off
	s_mov_b32 m0, s26
	s_nop 0
	global_load_lds_dwordx4 v[226:227], off
	s_waitcnt vmcnt(8)
	s_waitcnt lgkmcnt(0)
	s_barrier
	s_setprio 1
	s_waitcnt lgkmcnt(0)
	v_mfma_f32_16x16x32_bf16 v[62:65], v[146:149], v[178:181], v[62:65]
	v_mfma_f32_16x16x32_bf16 v[58:61], v[154:157], v[178:181], v[58:61]
	v_mfma_f32_16x16x32_bf16 v[46:49], v[146:149], v[186:189], v[46:49]
	v_mfma_f32_16x16x32_bf16 v[42:45], v[154:157], v[186:189], v[42:45]
	v_mfma_f32_16x16x32_bf16 v[30:33], v[146:149], v[194:197], v[30:33]
	v_mfma_f32_16x16x32_bf16 v[26:29], v[154:157], v[194:197], v[26:29]
	v_mfma_f32_16x16x32_bf16 v[14:17], v[146:149], v[202:205], v[14:17]
	v_mfma_f32_16x16x32_bf16 v[10:13], v[154:157], v[202:205], v[10:13]
	v_mfma_f32_16x16x32_bf16 v[62:65], v[150:153], v[182:185], v[62:65]
	v_mfma_f32_16x16x32_bf16 v[58:61], v[158:161], v[182:185], v[58:61]
	v_mfma_f32_16x16x32_bf16 v[46:49], v[150:153], v[190:193], v[46:49]
	v_mfma_f32_16x16x32_bf16 v[42:45], v[158:161], v[190:193], v[42:45]
	v_mfma_f32_16x16x32_bf16 v[30:33], v[150:153], v[198:201], v[30:33]
	v_mfma_f32_16x16x32_bf16 v[26:29], v[158:161], v[198:201], v[26:29]
	v_mfma_f32_16x16x32_bf16 v[14:17], v[150:153], v[222:225], v[14:17]
	v_mfma_f32_16x16x32_bf16 v[10:13], v[158:161], v[222:225], v[10:13]
	s_setprio 0
	s_setprio 1
	v_mfma_f32_16x16x32_bf16 v[54:57], v[162:165], v[178:181], v[54:57]
	v_mfma_f32_16x16x32_bf16 v[50:53], v[170:173], v[178:181], v[50:53]
	v_mfma_f32_16x16x32_bf16 v[38:41], v[162:165], v[186:189], v[38:41]
	v_mfma_f32_16x16x32_bf16 v[34:37], v[170:173], v[186:189], v[34:37]
	v_mfma_f32_16x16x32_bf16 v[22:25], v[162:165], v[194:197], v[22:25]
	v_mfma_f32_16x16x32_bf16 v[18:21], v[170:173], v[194:197], v[18:21]
	v_mfma_f32_16x16x32_bf16 v[6:9], v[162:165], v[202:205], v[6:9]
	v_mfma_f32_16x16x32_bf16 v[2:5], v[170:173], v[202:205], v[2:5]
	v_mfma_f32_16x16x32_bf16 v[54:57], v[166:169], v[182:185], v[54:57]
	v_mfma_f32_16x16x32_bf16 v[50:53], v[174:177], v[182:185], v[50:53]
	v_mfma_f32_16x16x32_bf16 v[38:41], v[166:169], v[190:193], v[38:41]
	v_mfma_f32_16x16x32_bf16 v[34:37], v[174:177], v[190:193], v[34:37]
	v_mfma_f32_16x16x32_bf16 v[22:25], v[166:169], v[198:201], v[22:25]
	v_mfma_f32_16x16x32_bf16 v[18:21], v[174:177], v[198:201], v[18:21]
	v_mfma_f32_16x16x32_bf16 v[6:9], v[166:169], v[222:225], v[6:9]
	v_mfma_f32_16x16x32_bf16 v[2:5], v[174:177], v[222:225], v[2:5]
	s_setprio 0
	s_barrier
	s_add_i32 s47, 0, 0x18000
	v_add_u32_e32 v0, s47, v135
	s_add_i32 s48, 0, 0x1c000
	ds_read_b128 v[146:149], v0
	ds_read_b128 v[150:153], v0 offset:1024
	ds_read_b128 v[154:157], v0 offset:2048
	ds_read_b128 v[158:161], v0 offset:3072
	v_add_u32_e32 v0, s48, v135
	ds_read_b128 v[162:165], v0
	ds_read_b128 v[166:169], v0 offset:1024
	ds_read_b128 v[170:173], v0 offset:2048
	ds_read_b128 v[174:177], v0 offset:3072
	s_add_u32 s18, s22, 0xb0000
	s_addc_u32 s19, s23, 0
	s_mov_b32 m0, s27
	v_lshl_add_u64 v[228:229], s[18:19], 0, v[130:131]
	ds_read_b128 v[178:181], v144 offset:32768
	ds_read_b128 v[182:185], v144 offset:33792
	ds_read_b128 v[186:189], v144 offset:34816
	ds_read_b128 v[190:193], v144 offset:35840
	ds_read_b128 v[194:197], v144 offset:36864
	ds_read_b128 v[198:201], v144 offset:37888
	ds_read_b128 v[202:205], v144 offset:38912
	ds_read_b128 v[222:225], v144 offset:39936
	global_load_lds_dwordx4 v[228:229], off
	v_lshl_add_u64 v[228:229], s[18:19], 0, v[132:133]
	s_mov_b32 m0, s28
	s_nop 0
	global_load_lds_dwordx4 v[228:229], off
	s_waitcnt vmcnt(8)
	s_waitcnt lgkmcnt(0)
	s_barrier
	s_setprio 1
	s_waitcnt lgkmcnt(0)
	v_mfma_f32_16x16x32_bf16 v[126:129], v[146:149], v[178:181], v[126:129]
	v_mfma_f32_16x16x32_bf16 v[122:125], v[154:157], v[178:181], v[122:125]
	v_mfma_f32_16x16x32_bf16 v[110:113], v[146:149], v[186:189], v[110:113]
	v_mfma_f32_16x16x32_bf16 v[106:109], v[154:157], v[186:189], v[106:109]
	v_mfma_f32_16x16x32_bf16 v[94:97], v[146:149], v[194:197], v[94:97]
	v_mfma_f32_16x16x32_bf16 v[90:93], v[154:157], v[194:197], v[90:93]
	v_mfma_f32_16x16x32_bf16 v[78:81], v[146:149], v[202:205], v[78:81]
	v_mfma_f32_16x16x32_bf16 v[74:77], v[154:157], v[202:205], v[74:77]
	v_mfma_f32_16x16x32_bf16 v[126:129], v[150:153], v[182:185], v[126:129]
	v_mfma_f32_16x16x32_bf16 v[122:125], v[158:161], v[182:185], v[122:125]
	v_mfma_f32_16x16x32_bf16 v[110:113], v[150:153], v[190:193], v[110:113]
	v_mfma_f32_16x16x32_bf16 v[106:109], v[158:161], v[190:193], v[106:109]
	v_mfma_f32_16x16x32_bf16 v[94:97], v[150:153], v[198:201], v[94:97]
	v_mfma_f32_16x16x32_bf16 v[90:93], v[158:161], v[198:201], v[90:93]
	v_mfma_f32_16x16x32_bf16 v[78:81], v[150:153], v[222:225], v[78:81]
	v_mfma_f32_16x16x32_bf16 v[74:77], v[158:161], v[222:225], v[74:77]
	s_setprio 0
	s_setprio 1
	v_mfma_f32_16x16x32_bf16 v[118:121], v[162:165], v[178:181], v[118:121]
	v_mfma_f32_16x16x32_bf16 v[114:117], v[170:173], v[178:181], v[114:117]
	v_mfma_f32_16x16x32_bf16 v[102:105], v[162:165], v[186:189], v[102:105]
	v_mfma_f32_16x16x32_bf16 v[98:101], v[170:173], v[186:189], v[98:101]
	v_mfma_f32_16x16x32_bf16 v[86:89], v[162:165], v[194:197], v[86:89]
	v_mfma_f32_16x16x32_bf16 v[82:85], v[170:173], v[194:197], v[82:85]
	v_mfma_f32_16x16x32_bf16 v[70:73], v[162:165], v[202:205], v[70:73]
	v_mfma_f32_16x16x32_bf16 v[66:69], v[170:173], v[202:205], v[66:69]
	v_mfma_f32_16x16x32_bf16 v[118:121], v[166:169], v[182:185], v[118:121]
	v_mfma_f32_16x16x32_bf16 v[114:117], v[174:177], v[182:185], v[114:117]
	v_mfma_f32_16x16x32_bf16 v[102:105], v[166:169], v[190:193], v[102:105]
	v_mfma_f32_16x16x32_bf16 v[98:101], v[174:177], v[190:193], v[98:101]
	v_mfma_f32_16x16x32_bf16 v[86:89], v[166:169], v[198:201], v[86:89]
	v_mfma_f32_16x16x32_bf16 v[82:85], v[174:177], v[198:201], v[82:85]
	v_mfma_f32_16x16x32_bf16 v[70:73], v[166:169], v[222:225], v[70:73]
	v_mfma_f32_16x16x32_bf16 v[66:69], v[174:177], v[222:225], v[66:69]
	s_setprio 0
	s_barrier
	s_add_i32 s18, s47, s24
	v_lshl_add_u64 v[142:143], v[142:143], 0, s[44:45]
	s_mov_b32 m0, s18
	ds_read_b128 v[178:181], v144 offset:49152
	ds_read_b128 v[182:185], v144 offset:50176
	ds_read_b128 v[186:189], v144 offset:51200
	ds_read_b128 v[190:193], v144 offset:52224
	ds_read_b128 v[194:197], v144 offset:53248
	ds_read_b128 v[198:201], v144 offset:54272
	ds_read_b128 v[202:205], v144 offset:55296
	ds_read_b128 v[222:225], v144 offset:56320
	global_load_lds_dwordx4 v[142:143], off
	s_add_i32 m0, s18, 0x2000
	s_add_u32 s18, s20, 0xb0080
	v_lshl_add_u64 v[142:143], v[206:207], 0, s[44:45]
	s_addc_u32 s19, s21, 0
	s_add_i32 s20, s48, s24
	global_load_lds_dwordx4 v[142:143], off
	v_lshl_add_u64 v[142:143], s[18:19], 0, v[130:131]
	s_mov_b32 m0, s20
	s_nop 0
	global_load_lds_dwordx4 v[142:143], off
	v_lshl_add_u64 v[142:143], s[18:19], 0, v[132:133]
	s_add_i32 m0, s20, 0x2000
	s_nop 0
	global_load_lds_dwordx4 v[142:143], off
	v_lshl_add_u64 v[142:143], v[218:219], 0, s[44:45]
	s_mov_b32 m0, s31
	s_nop 0
	global_load_lds_dwordx4 v[142:143], off
	v_lshl_add_u64 v[142:143], v[226:227], 0, s[44:45]
	s_mov_b32 m0, s33
	s_nop 0
	global_load_lds_dwordx4 v[142:143], off
	s_waitcnt vmcnt(8)
	s_waitcnt lgkmcnt(0)
	s_barrier
	s_setprio 1
	s_waitcnt lgkmcnt(0)
	v_mfma_f32_16x16x32_bf16 v[62:65], v[146:149], v[178:181], v[62:65]
	v_mfma_f32_16x16x32_bf16 v[58:61], v[154:157], v[178:181], v[58:61]
	v_mfma_f32_16x16x32_bf16 v[46:49], v[146:149], v[186:189], v[46:49]
	v_mfma_f32_16x16x32_bf16 v[42:45], v[154:157], v[186:189], v[42:45]
	v_mfma_f32_16x16x32_bf16 v[30:33], v[146:149], v[194:197], v[30:33]
	v_mfma_f32_16x16x32_bf16 v[26:29], v[154:157], v[194:197], v[26:29]
	v_mfma_f32_16x16x32_bf16 v[14:17], v[146:149], v[202:205], v[14:17]
	v_mfma_f32_16x16x32_bf16 v[10:13], v[154:157], v[202:205], v[10:13]
	v_mfma_f32_16x16x32_bf16 v[62:65], v[150:153], v[182:185], v[62:65]
	v_mfma_f32_16x16x32_bf16 v[58:61], v[158:161], v[182:185], v[58:61]
	v_mfma_f32_16x16x32_bf16 v[46:49], v[150:153], v[190:193], v[46:49]
	v_mfma_f32_16x16x32_bf16 v[42:45], v[158:161], v[190:193], v[42:45]
	v_mfma_f32_16x16x32_bf16 v[30:33], v[150:153], v[198:201], v[30:33]
	v_mfma_f32_16x16x32_bf16 v[26:29], v[158:161], v[198:201], v[26:29]
	v_mfma_f32_16x16x32_bf16 v[14:17], v[150:153], v[222:225], v[14:17]
	v_mfma_f32_16x16x32_bf16 v[10:13], v[158:161], v[222:225], v[10:13]
	s_setprio 0
	s_setprio 1
	v_mfma_f32_16x16x32_bf16 v[54:57], v[162:165], v[178:181], v[54:57]
	v_mfma_f32_16x16x32_bf16 v[50:53], v[170:173], v[178:181], v[50:53]
	v_mfma_f32_16x16x32_bf16 v[38:41], v[162:165], v[186:189], v[38:41]
	v_mfma_f32_16x16x32_bf16 v[34:37], v[170:173], v[186:189], v[34:37]
	v_mfma_f32_16x16x32_bf16 v[22:25], v[162:165], v[194:197], v[22:25]
	v_mfma_f32_16x16x32_bf16 v[18:21], v[170:173], v[194:197], v[18:21]
	v_mfma_f32_16x16x32_bf16 v[6:9], v[162:165], v[202:205], v[6:9]
	v_mfma_f32_16x16x32_bf16 v[2:5], v[170:173], v[202:205], v[2:5]
	v_mfma_f32_16x16x32_bf16 v[54:57], v[166:169], v[182:185], v[54:57]
	v_mfma_f32_16x16x32_bf16 v[50:53], v[174:177], v[182:185], v[50:53]
	v_mfma_f32_16x16x32_bf16 v[38:41], v[166:169], v[190:193], v[38:41]
	v_mfma_f32_16x16x32_bf16 v[34:37], v[174:177], v[190:193], v[34:37]
	v_mfma_f32_16x16x32_bf16 v[22:25], v[166:169], v[198:201], v[22:25]
	v_mfma_f32_16x16x32_bf16 v[18:21], v[174:177], v[198:201], v[18:21]
	v_mfma_f32_16x16x32_bf16 v[6:9], v[166:169], v[222:225], v[6:9]
	v_mfma_f32_16x16x32_bf16 v[2:5], v[174:177], v[222:225], v[2:5]
	s_add_i32 s46, s46, 2
	s_add_u32 s17, s17, 0x100
	s_addc_u32 s42, s42, 0
	s_mov_b64 s[18:19], s[2:3]
	s_cmp_gt_u32 s46, 41
	s_setprio 0
	s_barrier
	s_cbranch_scc0 .LBB0_849
	s_and_b64 vcc, exec, s[12:13]
	s_cbranch_vccz .LBB0_852
	s_barrier
